# transpose_item slow paths (P0 + layer-0 deferred conversions): gathers issued together instead of one dependent HBM round trip per load
# baseline (speedup 1.0000x reference)
.LBB0_16:
	v_mov_b32_e32 v60, 0
	v_mov_b32_e32 v61, 0
	v_mov_b32_e32 v62, 0
	v_mov_b32_e32 v63, 0
	v_mov_b32_e32 v64, 0
	v_mov_b32_e32 v65, 0
	v_mov_b32_e32 v66, 0
	v_mov_b32_e32 v67, 0
	v_mov_b32_e32 v68, 0
	v_mov_b32_e32 v69, 0
	v_mov_b32_e32 v70, 0
	v_mov_b32_e32 v71, 0
	v_mov_b32_e32 v72, 0
	v_mov_b32_e32 v73, 0
	v_mov_b32_e32 v74, 0
	v_mov_b32_e32 v75, 0
	v_mov_b32_e32 v76, 0
	v_mov_b32_e32 v77, 0
	v_mov_b32_e32 v78, 0
	v_mov_b32_e32 v79, 0
	v_mov_b32_e32 v80, 0
	v_mov_b32_e32 v81, 0
	v_mov_b32_e32 v82, 0
	v_mov_b32_e32 v83, 0
	v_mov_b32_e32 v84, 0
	v_mov_b32_e32 v85, 0
	v_mov_b32_e32 v86, 0
	v_mov_b32_e32 v87, 0
	v_mov_b32_e32 v88, 0
	v_mov_b32_e32 v89, 0
	v_mov_b32_e32 v90, 0
	v_mov_b32_e32 v91, 0
	s_and_saveexec_b64 s[14:15], vcc
	s_cbranch_execz .Lt80_p0_skip
	v_readlane_b32 s36, v253, 15
	v_readlane_b32 s37, v253, 16
	v_readlane_b32 s38, v253, 17
	v_readlane_b32 s39, v253, 18
	v_readlane_b32 s40, v253, 19
	v_readlane_b32 s41, v253, 20
	v_readlane_b32 s42, v253, 21
	v_readlane_b32 s43, v253, 22
	v_readlane_b32 s44, v253, 23
	v_readlane_b32 s45, v253, 24
	v_readlane_b32 s46, v253, 25
	v_readlane_b32 s47, v253, 26
	v_readlane_b32 s48, v253, 27
	v_readlane_b32 s49, v253, 28
	v_readlane_b32 s50, v253, 29
	v_readlane_b32 s51, v253, 30
	v_lshl_add_u64 v[58:59], v[4:5], 2, s[36:37]
	global_load_dword v60, v[58:59], off
	v_lshl_add_u64 v[58:59], v[22:23], 0, s[12:13]
	global_load_dword v61, v[58:59], off
	v_lshl_add_u64 v[58:59], v[20:21], 0, s[12:13]
	global_load_dword v62, v[58:59], off
	v_lshl_add_u64 v[58:59], v[18:19], 0, s[12:13]
	global_load_dword v63, v[58:59], off
	v_lshl_add_u64 v[58:59], v[16:17], 0, s[12:13]
	global_load_dword v64, v[58:59], off
	v_lshl_add_u64 v[58:59], v[14:15], 0, s[12:13]
	global_load_dword v65, v[58:59], off
	v_lshl_add_u64 v[58:59], v[12:13], 0, s[12:13]
	global_load_dword v66, v[58:59], off
	v_lshl_add_u64 v[58:59], v[10:11], 0, s[12:13]
	global_load_dword v67, v[58:59], off
	s_add_u32 s12, s12, 0xb9400
	s_addc_u32 s13, s13, 0
	v_add_u32_e32 v4, 0x2e500, v4
	v_lshl_add_u64 v[58:59], v[4:5], 2, s[36:37]
	global_load_dword v68, v[58:59], off
	v_lshl_add_u64 v[58:59], v[22:23], 0, s[12:13]
	global_load_dword v69, v[58:59], off
	v_lshl_add_u64 v[58:59], v[20:21], 0, s[12:13]
	global_load_dword v70, v[58:59], off
	v_lshl_add_u64 v[58:59], v[18:19], 0, s[12:13]
	global_load_dword v71, v[58:59], off
	v_lshl_add_u64 v[58:59], v[16:17], 0, s[12:13]
	global_load_dword v72, v[58:59], off
	v_lshl_add_u64 v[58:59], v[14:15], 0, s[12:13]
	global_load_dword v73, v[58:59], off
	v_lshl_add_u64 v[58:59], v[12:13], 0, s[12:13]
	global_load_dword v74, v[58:59], off
	v_lshl_add_u64 v[58:59], v[10:11], 0, s[12:13]
	global_load_dword v75, v[58:59], off
	s_add_u32 s12, s12, 0xb9400
	s_addc_u32 s13, s13, 0
	v_add_u32_e32 v4, 0x2e500, v4
	v_lshl_add_u64 v[58:59], v[4:5], 2, s[36:37]
	global_load_dword v76, v[58:59], off
	v_lshl_add_u64 v[58:59], v[22:23], 0, s[12:13]
	global_load_dword v77, v[58:59], off
	v_lshl_add_u64 v[58:59], v[20:21], 0, s[12:13]
	global_load_dword v78, v[58:59], off
	v_lshl_add_u64 v[58:59], v[18:19], 0, s[12:13]
	global_load_dword v79, v[58:59], off
	v_lshl_add_u64 v[58:59], v[16:17], 0, s[12:13]
	global_load_dword v80, v[58:59], off
	v_lshl_add_u64 v[58:59], v[14:15], 0, s[12:13]
	global_load_dword v81, v[58:59], off
	v_lshl_add_u64 v[58:59], v[12:13], 0, s[12:13]
	global_load_dword v82, v[58:59], off
	v_lshl_add_u64 v[58:59], v[10:11], 0, s[12:13]
	global_load_dword v83, v[58:59], off
	s_add_u32 s12, s12, 0xb9400
	s_addc_u32 s13, s13, 0
	v_add_u32_e32 v4, 0x2e500, v4
	v_lshl_add_u64 v[58:59], v[4:5], 2, s[36:37]
	global_load_dword v84, v[58:59], off
	v_lshl_add_u64 v[58:59], v[22:23], 0, s[12:13]
	global_load_dword v85, v[58:59], off
	v_lshl_add_u64 v[58:59], v[20:21], 0, s[12:13]
	global_load_dword v86, v[58:59], off
	v_lshl_add_u64 v[58:59], v[18:19], 0, s[12:13]
	global_load_dword v87, v[58:59], off
	v_lshl_add_u64 v[58:59], v[16:17], 0, s[12:13]
	global_load_dword v88, v[58:59], off
	v_lshl_add_u64 v[58:59], v[14:15], 0, s[12:13]
	global_load_dword v89, v[58:59], off
	v_lshl_add_u64 v[58:59], v[12:13], 0, s[12:13]
	global_load_dword v90, v[58:59], off
	v_lshl_add_u64 v[58:59], v[10:11], 0, s[12:13]
	global_load_dword v91, v[58:59], off
	s_add_u32 s12, s12, 0xb9400
	s_addc_u32 s13, s13, 0
	v_add_u32_e32 v4, 0x2e500, v4
.Lt80_p0_skip:
	s_or_b64 exec, exec, s[14:15]
	s_waitcnt vmcnt(0)
	ds_write_b32 v56, v60
	ds_write_b32 v56, v61 offset:264
	ds_write_b32 v56, v62 offset:528
	ds_write_b32 v56, v63 offset:792
	ds_write_b32 v56, v64 offset:1056
	ds_write_b32 v56, v65 offset:1320
	ds_write_b32 v56, v66 offset:1584
	ds_write_b32 v56, v67 offset:1848
	v_add_u32_e32 v56, 0x840, v56
	ds_write_b32 v56, v68
	ds_write_b32 v56, v69 offset:264
	ds_write_b32 v56, v70 offset:528
	ds_write_b32 v56, v71 offset:792
	ds_write_b32 v56, v72 offset:1056
	ds_write_b32 v56, v73 offset:1320
	ds_write_b32 v56, v74 offset:1584
	ds_write_b32 v56, v75 offset:1848
	v_add_u32_e32 v56, 0x840, v56
	ds_write_b32 v56, v76
	ds_write_b32 v56, v77 offset:264
	ds_write_b32 v56, v78 offset:528
	ds_write_b32 v56, v79 offset:792
	ds_write_b32 v56, v80 offset:1056
	ds_write_b32 v56, v81 offset:1320
	ds_write_b32 v56, v82 offset:1584
	ds_write_b32 v56, v83 offset:1848
	v_add_u32_e32 v56, 0x840, v56
	ds_write_b32 v56, v84
	ds_write_b32 v56, v85 offset:264
	ds_write_b32 v56, v86 offset:528
	ds_write_b32 v56, v87 offset:792
	ds_write_b32 v56, v88 offset:1056
	ds_write_b32 v56, v89 offset:1320
	ds_write_b32 v56, v90 offset:1584
	ds_write_b32 v56, v91 offset:1848

.LBB0_186:
	v_mov_b32_e32 v72, 0
	v_mov_b32_e32 v73, 0
	v_mov_b32_e32 v74, 0
	v_mov_b32_e32 v75, 0
	v_mov_b32_e32 v76, 0
	v_mov_b32_e32 v77, 0
	v_mov_b32_e32 v78, 0
	v_mov_b32_e32 v79, 0
	v_mov_b32_e32 v80, 0
	v_mov_b32_e32 v81, 0
	v_mov_b32_e32 v82, 0
	v_mov_b32_e32 v83, 0
	v_mov_b32_e32 v84, 0
	v_mov_b32_e32 v85, 0
	v_mov_b32_e32 v86, 0
	v_mov_b32_e32 v87, 0
	v_mov_b32_e32 v88, 0
	v_mov_b32_e32 v89, 0
	v_mov_b32_e32 v90, 0
	v_mov_b32_e32 v91, 0
	v_mov_b32_e32 v92, 0
	v_mov_b32_e32 v93, 0
	v_mov_b32_e32 v94, 0
	v_mov_b32_e32 v95, 0
	v_mov_b32_e32 v96, 0
	v_mov_b32_e32 v97, 0
	v_mov_b32_e32 v98, 0
	v_mov_b32_e32 v99, 0
	v_mov_b32_e32 v100, 0
	v_mov_b32_e32 v101, 0
	v_mov_b32_e32 v102, 0
	v_mov_b32_e32 v103, 0
	s_and_saveexec_b64 s[8:9], vcc
	s_cbranch_execz .Lt80_c1e_skip
	v_readlane_b32 s24, v253, 52
	v_mov_b32_e32 v31, v4
	v_readlane_b32 s25, v253, 53
	s_nop 1
	v_lshl_add_u64 v[70:71], v[30:31], 2, s[24:25]
	global_load_dword v72, v[70:71], off
	v_lshl_add_u64 v[70:71], v[28:29], 0, s[6:7]
	global_load_dword v73, v[70:71], off
	v_lshl_add_u64 v[70:71], v[26:27], 0, s[6:7]
	global_load_dword v74, v[70:71], off
	v_lshl_add_u64 v[70:71], v[24:25], 0, s[6:7]
	global_load_dword v75, v[70:71], off
	v_lshl_add_u64 v[70:71], v[22:23], 0, s[6:7]
	global_load_dword v76, v[70:71], off
	v_lshl_add_u64 v[70:71], v[20:21], 0, s[6:7]
	global_load_dword v77, v[70:71], off
	v_lshl_add_u64 v[70:71], v[18:19], 0, s[6:7]
	global_load_dword v78, v[70:71], off
	v_lshl_add_u64 v[70:71], v[16:17], 0, s[6:7]
	global_load_dword v79, v[70:71], off
	s_add_u32 s6, s6, 0xb9400
	s_addc_u32 s7, s7, 0
	v_add_u32_e32 v30, 0x2e500, v30
	v_lshl_add_u64 v[70:71], v[30:31], 2, s[24:25]
	global_load_dword v80, v[70:71], off
	v_lshl_add_u64 v[70:71], v[28:29], 0, s[6:7]
	global_load_dword v81, v[70:71], off
	v_lshl_add_u64 v[70:71], v[26:27], 0, s[6:7]
	global_load_dword v82, v[70:71], off
	v_lshl_add_u64 v[70:71], v[24:25], 0, s[6:7]
	global_load_dword v83, v[70:71], off
	v_lshl_add_u64 v[70:71], v[22:23], 0, s[6:7]
	global_load_dword v84, v[70:71], off
	v_lshl_add_u64 v[70:71], v[20:21], 0, s[6:7]
	global_load_dword v85, v[70:71], off
	v_lshl_add_u64 v[70:71], v[18:19], 0, s[6:7]
	global_load_dword v86, v[70:71], off
	v_lshl_add_u64 v[70:71], v[16:17], 0, s[6:7]
	global_load_dword v87, v[70:71], off
	s_add_u32 s6, s6, 0xb9400
	s_addc_u32 s7, s7, 0
	v_add_u32_e32 v30, 0x2e500, v30
	v_lshl_add_u64 v[70:71], v[30:31], 2, s[24:25]
	global_load_dword v88, v[70:71], off
	v_lshl_add_u64 v[70:71], v[28:29], 0, s[6:7]
	global_load_dword v89, v[70:71], off
	v_lshl_add_u64 v[70:71], v[26:27], 0, s[6:7]
	global_load_dword v90, v[70:71], off
	v_lshl_add_u64 v[70:71], v[24:25], 0, s[6:7]
	global_load_dword v91, v[70:71], off
	v_lshl_add_u64 v[70:71], v[22:23], 0, s[6:7]
	global_load_dword v92, v[70:71], off
	v_lshl_add_u64 v[70:71], v[20:21], 0, s[6:7]
	global_load_dword v93, v[70:71], off
	v_lshl_add_u64 v[70:71], v[18:19], 0, s[6:7]
	global_load_dword v94, v[70:71], off
	v_lshl_add_u64 v[70:71], v[16:17], 0, s[6:7]
	global_load_dword v95, v[70:71], off
	s_add_u32 s6, s6, 0xb9400
	s_addc_u32 s7, s7, 0
	v_add_u32_e32 v30, 0x2e500, v30
	v_lshl_add_u64 v[70:71], v[30:31], 2, s[24:25]
	global_load_dword v96, v[70:71], off
	v_lshl_add_u64 v[70:71], v[28:29], 0, s[6:7]
	global_load_dword v97, v[70:71], off
	v_lshl_add_u64 v[70:71], v[26:27], 0, s[6:7]
	global_load_dword v98, v[70:71], off
	v_lshl_add_u64 v[70:71], v[24:25], 0, s[6:7]
	global_load_dword v99, v[70:71], off
	v_lshl_add_u64 v[70:71], v[22:23], 0, s[6:7]
	global_load_dword v100, v[70:71], off
	v_lshl_add_u64 v[70:71], v[20:21], 0, s[6:7]
	global_load_dword v101, v[70:71], off
	v_lshl_add_u64 v[70:71], v[18:19], 0, s[6:7]
	global_load_dword v102, v[70:71], off
	v_lshl_add_u64 v[70:71], v[16:17], 0, s[6:7]
	global_load_dword v103, v[70:71], off
	s_add_u32 s6, s6, 0xb9400
	s_addc_u32 s7, s7, 0
	v_add_u32_e32 v30, 0x2e500, v30
.Lt80_c1e_skip:
	s_or_b64 exec, exec, s[8:9]
	s_waitcnt vmcnt(0)
	ds_write_b32 v67, v72
	ds_write_b32 v67, v73 offset:264
	ds_write_b32 v67, v74 offset:528
	ds_write_b32 v67, v75 offset:792
	ds_write_b32 v67, v76 offset:1056
	ds_write_b32 v67, v77 offset:1320
	ds_write_b32 v67, v78 offset:1584
	ds_write_b32 v67, v79 offset:1848
	v_add_u32_e32 v67, 0x840, v67
	ds_write_b32 v67, v80
	ds_write_b32 v67, v81 offset:264
	ds_write_b32 v67, v82 offset:528
	ds_write_b32 v67, v83 offset:792
	ds_write_b32 v67, v84 offset:1056
	ds_write_b32 v67, v85 offset:1320
	ds_write_b32 v67, v86 offset:1584
	ds_write_b32 v67, v87 offset:1848
	v_add_u32_e32 v67, 0x840, v67
	ds_write_b32 v67, v88
	ds_write_b32 v67, v89 offset:264
	ds_write_b32 v67, v90 offset:528
	ds_write_b32 v67, v91 offset:792
	ds_write_b32 v67, v92 offset:1056
	ds_write_b32 v67, v93 offset:1320
	ds_write_b32 v67, v94 offset:1584
	ds_write_b32 v67, v95 offset:1848
	v_add_u32_e32 v67, 0x840, v67
	ds_write_b32 v67, v96
	ds_write_b32 v67, v97 offset:264
	ds_write_b32 v67, v98 offset:528
	ds_write_b32 v67, v99 offset:792
	ds_write_b32 v67, v100 offset:1056
	ds_write_b32 v67, v101 offset:1320
	ds_write_b32 v67, v102 offset:1584
	ds_write_b32 v67, v103 offset:1848

.LBB0_205:
	s_lshl_b32 s27, s24, 1
	s_lshl_b32 s26, s22, 1
	v_or_b32_e32 v22, s27, v6
	v_or_b32_e32 v17, s26, v1
	v_add_u32_e32 v20, s8, v22
	v_add_u32_e32 v18, s23, v17
	v_mad_u64_u32 v[20:21], s[28:29], v20, s31, v[16:17]
	v_mad_u64_u32 v[18:19], s[28:29], v18, s31, v[16:17]
	v_mov_b32_e32 v21, v4
	v_lshl_add_u64 v[20:21], v[20:21], 2, s[6:7]
	v_mov_b32_e32 v19, v4
	v_lshl_add_u64 v[18:19], v[18:19], 2, s[6:7]
	global_load_dword v72, v[20:21], off
	global_load_dword v73, v[18:19], off
	v_mad_u64_u32 v[18:19], s[28:29], v22, s30, v[8:9]
	v_mad_u64_u32 v[20:21], s[28:29], v17, s30, v[8:9]
	s_add_i32 s29, s27, 4
	s_add_i32 s28, s26, 4
	v_or_b32_e32 v22, s29, v6
	v_or_b32_e32 v17, s28, v1
	s_add_i32 s24, s24, 16
	s_add_i32 s22, s22, 16
	s_add_i32 s25, s25, -16
	v_mov_b32_e32 v74, v18
	v_mov_b32_e32 v75, v20
	v_add_u32_e32 v20, s8, v22
	v_add_u32_e32 v18, s23, v17
	v_mad_u64_u32 v[20:21], s[28:29], v20, s31, v[16:17]
	v_mad_u64_u32 v[18:19], s[28:29], v18, s31, v[16:17]
	v_mov_b32_e32 v21, v4
	v_lshl_add_u64 v[20:21], v[20:21], 2, s[6:7]
	v_mov_b32_e32 v19, v4
	v_lshl_add_u64 v[18:19], v[18:19], 2, s[6:7]
	global_load_dword v76, v[20:21], off
	global_load_dword v77, v[18:19], off
	v_mad_u64_u32 v[18:19], s[28:29], v22, s30, v[8:9]
	v_mad_u64_u32 v[20:21], s[28:29], v17, s30, v[8:9]
	s_add_i32 s29, s27, 8
	s_add_i32 s28, s26, 8
	v_or_b32_e32 v22, s29, v6
	v_or_b32_e32 v17, s28, v1
	v_mov_b32_e32 v78, v18
	v_mov_b32_e32 v79, v20
	v_add_u32_e32 v20, s8, v22
	v_add_u32_e32 v18, s23, v17
	v_mad_u64_u32 v[20:21], s[28:29], v20, s31, v[16:17]
	v_mad_u64_u32 v[18:19], s[28:29], v18, s31, v[16:17]
	v_mov_b32_e32 v21, v4
	v_lshl_add_u64 v[20:21], v[20:21], 2, s[6:7]
	v_mov_b32_e32 v19, v4
	v_lshl_add_u64 v[18:19], v[18:19], 2, s[6:7]
	global_load_dword v80, v[20:21], off
	global_load_dword v81, v[18:19], off
	v_mad_u64_u32 v[18:19], s[28:29], v22, s30, v[8:9]
	v_mad_u64_u32 v[20:21], s[28:29], v17, s30, v[8:9]
	s_add_i32 s29, s27, 12
	s_add_i32 s28, s26, 12
	v_or_b32_e32 v22, s29, v6
	v_or_b32_e32 v17, s28, v1
	v_mov_b32_e32 v82, v18
	v_mov_b32_e32 v83, v20
	v_add_u32_e32 v20, s8, v22
	v_add_u32_e32 v18, s23, v17
	v_mad_u64_u32 v[20:21], s[28:29], v20, s31, v[16:17]
	v_mad_u64_u32 v[18:19], s[28:29], v18, s31, v[16:17]
	v_mov_b32_e32 v21, v4
	v_lshl_add_u64 v[20:21], v[20:21], 2, s[6:7]
	v_mov_b32_e32 v19, v4
	v_lshl_add_u64 v[18:19], v[18:19], 2, s[6:7]
	global_load_dword v84, v[20:21], off
	global_load_dword v85, v[18:19], off
	v_mad_u64_u32 v[18:19], s[28:29], v22, s30, v[8:9]
	v_mad_u64_u32 v[20:21], s[28:29], v17, s30, v[8:9]
	s_add_i32 s29, s27, 16
	s_add_i32 s28, s26, 16
	v_or_b32_e32 v22, s29, v6
	v_or_b32_e32 v17, s28, v1
	v_mov_b32_e32 v86, v18
	v_mov_b32_e32 v87, v20
	v_add_u32_e32 v20, s8, v22
	v_add_u32_e32 v18, s23, v17
	v_mad_u64_u32 v[20:21], s[28:29], v20, s31, v[16:17]
	v_mad_u64_u32 v[18:19], s[28:29], v18, s31, v[16:17]
	v_mov_b32_e32 v21, v4
	v_lshl_add_u64 v[20:21], v[20:21], 2, s[6:7]
	v_mov_b32_e32 v19, v4
	v_lshl_add_u64 v[18:19], v[18:19], 2, s[6:7]
	global_load_dword v88, v[20:21], off
	global_load_dword v89, v[18:19], off
	v_mad_u64_u32 v[18:19], s[28:29], v22, s30, v[8:9]
	v_mad_u64_u32 v[20:21], s[28:29], v17, s30, v[8:9]
	s_add_i32 s29, s27, 20
	s_add_i32 s28, s26, 20
	v_or_b32_e32 v22, s29, v6
	v_or_b32_e32 v17, s28, v1
	v_mov_b32_e32 v90, v18
	v_mov_b32_e32 v91, v20
	v_add_u32_e32 v20, s8, v22
	v_add_u32_e32 v18, s23, v17
	v_mad_u64_u32 v[20:21], s[28:29], v20, s31, v[16:17]
	v_mad_u64_u32 v[18:19], s[28:29], v18, s31, v[16:17]
	v_mov_b32_e32 v21, v4
	v_lshl_add_u64 v[20:21], v[20:21], 2, s[6:7]
	v_mov_b32_e32 v19, v4
	v_lshl_add_u64 v[18:19], v[18:19], 2, s[6:7]
	global_load_dword v92, v[20:21], off
	global_load_dword v93, v[18:19], off
	v_mad_u64_u32 v[18:19], s[28:29], v22, s30, v[8:9]
	v_mad_u64_u32 v[20:21], s[28:29], v17, s30, v[8:9]
	s_add_i32 s29, s27, 24
	s_add_i32 s28, s26, 24
	v_or_b32_e32 v22, s29, v6
	v_or_b32_e32 v17, s28, v1
	s_add_i32 s27, s27, 28
	s_add_i32 s26, s26, 28
	s_cmp_lg_u32 s25, 0
	v_mov_b32_e32 v94, v18
	v_mov_b32_e32 v95, v20
	v_add_u32_e32 v20, s8, v22
	v_add_u32_e32 v18, s23, v17
	v_mad_u64_u32 v[20:21], s[28:29], v20, s31, v[16:17]
	v_mad_u64_u32 v[18:19], s[28:29], v18, s31, v[16:17]
	v_mov_b32_e32 v21, v4
	v_lshl_add_u64 v[20:21], v[20:21], 2, s[6:7]
	v_mov_b32_e32 v19, v4
	v_lshl_add_u64 v[18:19], v[18:19], 2, s[6:7]
	global_load_dword v96, v[20:21], off
	global_load_dword v97, v[18:19], off
	v_mad_u64_u32 v[18:19], s[28:29], v22, s30, v[8:9]
	v_mad_u64_u32 v[20:21], s[28:29], v17, s30, v[8:9]
	v_or_b32_e32 v22, s27, v6
	v_or_b32_e32 v17, s26, v1
	v_mov_b32_e32 v98, v18
	v_mov_b32_e32 v99, v20
	v_add_u32_e32 v20, s8, v22
	v_add_u32_e32 v18, s23, v17
	v_mad_u64_u32 v[20:21], s[26:27], v20, s31, v[16:17]
	v_mad_u64_u32 v[18:19], s[26:27], v18, s31, v[16:17]
	v_mov_b32_e32 v21, v4
	v_lshl_add_u64 v[20:21], v[20:21], 2, s[6:7]
	v_mov_b32_e32 v19, v4
	v_lshl_add_u64 v[18:19], v[18:19], 2, s[6:7]
	global_load_dword v100, v[20:21], off
	global_load_dword v101, v[18:19], off
	v_mad_u64_u32 v[18:19], s[26:27], v22, s30, v[8:9]
	v_mad_u64_u32 v[20:21], s[26:27], v17, s30, v[8:9]
	v_mov_b32_e32 v102, v18
	v_mov_b32_e32 v103, v20
	s_waitcnt vmcnt(0)
	ds_write_b32 v74, v72
	ds_write_b32 v75, v73
	ds_write_b32 v78, v76
	ds_write_b32 v79, v77
	ds_write_b32 v82, v80
	ds_write_b32 v83, v81
	ds_write_b32 v86, v84
	ds_write_b32 v87, v85
	ds_write_b32 v90, v88
	ds_write_b32 v91, v89
	ds_write_b32 v94, v92
	ds_write_b32 v95, v93
	ds_write_b32 v98, v96
	ds_write_b32 v99, v97
	ds_write_b32 v102, v100
	ds_write_b32 v103, v101
	s_cbranch_scc1 .LBB0_205
	s_waitcnt lgkmcnt(0)
	s_mul_i32 s7, s9, 0x600000
	s_mul_hi_u32 s6, s9, 0x600000
	s_add_u32 s7, s3, s7
	ds_read2_b32 v[18:19], v7 offset1:33
	s_addc_u32 s9, s10, s6
	s_and_b32 s6, 0xffff, s8
	s_waitcnt lgkmcnt(0)
	v_cvt_pk_bf16_f32 v18, v18, v19
	ds_read2_b32 v[20:21], v7 offset0:66 offset1:99
	s_bitset1_b32 s21, 11
	s_lshl_b32 s6, s6, 1
	s_waitcnt lgkmcnt(0)
	v_cvt_pk_bf16_f32 v19, v20, v21
	ds_read2_b32 v[20:21], v7 offset0:132 offset1:165
	s_add_u32 s6, s7, s6
	s_waitcnt lgkmcnt(0)
	v_cvt_pk_bf16_f32 v20, v20, v21
	ds_read2_b32 v[22:23], v7 offset0:198 offset1:231
	s_addc_u32 s7, s9, 0
	v_lshlrev_b32_e32 v16, 1, v10
	v_mov_b32_e32 v17, v4
	s_waitcnt lgkmcnt(0)
	v_cvt_pk_bf16_f32 v21, v22, v23
	v_or_b32_e32 v22, s21, v5
	v_lshl_add_u64 v[16:17], s[6:7], 0, v[16:17]
	v_lshlrev_b32_e32 v22, 11, v22
	v_mov_b32_e32 v23, v4
	v_lshl_add_u64 v[22:23], v[16:17], 0, v[22:23]
	global_store_dwordx4 v[22:23], v[18:21], off
	ds_read2_b32 v[18:19], v7 offset0:8 offset1:41
	s_mov_b32 s51, 0x40c000
	s_waitcnt lgkmcnt(0)
	v_cvt_pk_bf16_f32 v18, v18, v19
	ds_read2_b32 v[20:21], v7 offset0:74 offset1:107
	s_waitcnt lgkmcnt(0)
	v_cvt_pk_bf16_f32 v19, v20, v21
	ds_read2_b32 v[20:21], v7 offset0:140 offset1:173
	s_waitcnt lgkmcnt(0)
	v_cvt_pk_bf16_f32 v20, v20, v21
	ds_read2_b32 v[22:23], v7 offset0:206 offset1:239
	s_waitcnt lgkmcnt(0)
	v_cvt_pk_bf16_f32 v21, v22, v23
	v_or_b32_e32 v22, s21, v9
	v_lshlrev_b32_e32 v22, 11, v22
	v_mov_b32_e32 v23, v4
	v_lshl_add_u64 v[22:23], v[16:17], 0, v[22:23]
	global_store_dwordx4 v[22:23], v[18:21], off
	ds_read2_b32 v[18:19], v7 offset0:16 offset1:49
	s_mov_b64 s[48:49], 0x7ffff
	s_waitcnt lgkmcnt(0)
	v_cvt_pk_bf16_f32 v18, v18, v19
	ds_read2_b32 v[20:21], v7 offset0:82 offset1:115
	s_waitcnt lgkmcnt(0)
	v_cvt_pk_bf16_f32 v19, v20, v21
	ds_read2_b32 v[20:21], v7 offset0:148 offset1:181
	s_waitcnt lgkmcnt(0)
	v_cvt_pk_bf16_f32 v20, v20, v21
	ds_read2_b32 v[22:23], v7 offset0:214 offset1:247
	s_waitcnt lgkmcnt(0)
	v_cvt_pk_bf16_f32 v21, v22, v23
	v_or_b32_e32 v22, s21, v11
	v_lshlrev_b32_e32 v22, 11, v22
	v_mov_b32_e32 v23, v4
	v_lshl_add_u64 v[22:23], v[16:17], 0, v[22:23]
	global_store_dwordx4 v[22:23], v[18:21], off
	ds_read2_b32 v[18:19], v7 offset0:24 offset1:57
	s_waitcnt lgkmcnt(0)
	v_cvt_pk_bf16_f32 v18, v18, v19
	ds_read2_b32 v[20:21], v7 offset0:90 offset1:123
	s_waitcnt lgkmcnt(0)
	v_cvt_pk_bf16_f32 v19, v20, v21
	ds_read2_b32 v[20:21], v7 offset0:156 offset1:189
	s_waitcnt lgkmcnt(0)
	v_cvt_pk_bf16_f32 v20, v20, v21
	ds_read2_b32 v[22:23], v7 offset0:222 offset1:255
	s_waitcnt lgkmcnt(0)
	v_cvt_pk_bf16_f32 v21, v22, v23
	v_or_b32_e32 v22, s21, v32
	v_lshlrev_b32_e32 v22, 11, v22
	v_mov_b32_e32 v23, v4
	v_lshl_add_u64 v[16:17], v[16:17], 0, v[22:23]
	global_store_dwordx4 v[16:17], v[18:21], off
	s_waitcnt lgkmcnt(0)
